# stagger order reversed: group 7 starts first, group 0 last (g x ~3.5 us)
# baseline (speedup 1.0000x reference)
; __device__ __forceinline__ void xcd_barrier(const XcdBarrier& b) {
;     ...
;     __syncthreads();
; __global__ void __launch_bounds__(NWAVES * 64, 2) fwd_kernel(Args args) {
;     ...
;         if (ph + 1 < args.ph_hi || rep + 1 < nrep) { if (args.ph_hi > 1000) grid.sync(); else xcd_barrier(xb); } else __syncthreads();
.LBB0_486:
	s_or_b64 exec, exec, s[26:27]
	s_cmp_eq_u32 s10, 1
	s_cbranch_scc0 stg_skip
	s_and_b32 s2, s89, 7
	s_sub_u32 s2, 7, s2
